# in-proj GEMM tile assignment: workgroups c and c^1 exchange tiles on odd rounds so each workgroup gets one tile of every column segment (balances the per-segment epilogue costs)
# speedup vs baseline: 1.0039x; 1.0039x over previous
.LBB0_124:
	s_add_i32 s54, s54, 1
	v_readlane_b32 s3, v251, 21
	s_mul_i32 s3, s54, s3
	s_mul_hi_u32 s21, s54, s70
	s_add_i32 s21, s21, s3
	s_mul_i32 s3, s54, s70
	s_and_b32 s24, s54, 1
	s_xor_b32 s24, s24, s67
	s_add_u32 s24, s3, s24
	v_readlane_b32 s3, v251, 18
	s_addc_u32 s25, s21, s3
	v_mov_b64_e32 v[2:3], 0x400
	v_cmp_lt_i64_e64 s[90:91], s[24:25], v[2:3]
	v_mov_b64_e32 v[2:3], 0x3ff
	v_cmp_gt_i64_e32 vcc, s[24:25], v[2:3]
	s_cbranch_vccnz .LBB0_130
	s_ashr_i32 s3, s24, 31
	s_lshr_b32 s3, s3, 29
	s_add_i32 s3, s24, s3
	s_and_b32 s20, s3, -8
	s_sub_i32 s22, s24, s20
	s_cmp_gt_i32 s22, -1
	s_mov_b64 s[20:21], -1
	s_cbranch_scc0 .LBB0_127
	s_lshl_b32 s23, s22, 7
	s_mov_b64 s[20:21], 0

.LBB0_405:
	s_add_i32 s53, s53, 1
	v_readlane_b32 s6, v251, 21
	s_mul_i32 s6, s53, s6
	s_mul_hi_u32 s7, s53, s70
	s_add_i32 s7, s7, s6
	s_mul_i32 s6, s53, s70
	s_and_b32 s21, s53, 1
	s_xor_b32 s21, s21, s67
	s_add_u32 s6, s6, s21
	v_readlane_b32 s21, v251, 18
	s_addc_u32 s7, s7, s21
	v_mov_b64_e32 v[2:3], 0x600
	v_cmp_lt_i64_e64 s[88:89], s[6:7], v[2:3]
	v_mov_b64_e32 v[2:3], 0x5ff
	v_cmp_gt_i64_e32 vcc, s[6:7], v[2:3]
	s_cbranch_vccnz .LBB0_407
	s_ashr_i32 s7, s6, 31
	s_lshr_b32 s7, s7, 29
	s_add_i32 s7, s6, s7
	s_ashr_i32 s20, s7, 3
	s_and_b32 s7, s7, -8
	s_sub_i32 s6, s6, s7
	s_cmp_lt_i32 s6, 0
	s_movk_i32 s7, 0xc1
	s_cselect_b32 s7, s7, 0xc0
	s_mul_i32 s6, s6, s7
	s_add_i32 s6, s6, s20
	s_mul_hi_i32 s7, s6, 0x2aaaaaab
	s_lshr_b32 s20, s7, 31
	s_ashr_i32 s7, s7, 6
	s_add_i32 s7, s7, s20
	s_lshl_b32 s21, s7, 3
	s_sub_i32 s20, 32, s21
	s_min_i32 s22, s20, 8
	s_abs_i32 s20, s22
	v_cvt_f32_u32_e32 v2, s20
	s_sub_i32 s24, 0, s20
	s_mulk_i32 s7, 0x180
	s_sub_i32 s6, s6, s7
	v_rcp_iflag_f32_e32 v2, v2
	s_abs_i32 s7, s6
	s_xor_b32 s23, s6, s22
	s_ashr_i32 s23, s23, 31
	v_mul_f32_e32 v2, 0x4f7ffffe, v2
	v_cvt_u32_f32_e32 v2, v2
	s_nop 0
	v_readfirstlane_b32 s25, v2
	s_mul_i32 s24, s24, s25
	s_mul_hi_u32 s24, s25, s24
	s_add_i32 s25, s25, s24
	s_mul_hi_u32 s24, s7, s25
	s_mul_i32 s25, s24, s20
	s_sub_i32 s7, s7, s25
	s_add_i32 s26, s24, 1
	s_sub_i32 s25, s7, s20
	s_cmp_ge_u32 s7, s20
	s_cselect_b32 s24, s26, s24
	s_cselect_b32 s7, s25, s7
	s_add_i32 s25, s24, 1
	s_cmp_ge_u32 s7, s20
	s_cselect_b32 s7, s25, s24
	s_xor_b32 s7, s7, s23
	s_sub_i32 s20, s7, s23
	s_mul_i32 s7, s20, s22
	s_sub_i32 s6, s6, s7
	s_add_i32 s22, s21, s6
